# plus diff-attention far-stage body hand-scheduled (V prefetch, exp/PV interleave) and diff epilogue gain loads de-serialized
# baseline (speedup 1.0000x reference)
; DI f32x16 mfma32(bf16x8 a, bf16x8 b, f32x16 c) { return __builtin_amdgcn_mfma_f32_32x32x16_bf16(a, b, c, 0, 0, 0); }
; DI void diff_map_far2(const unsigned char* sk, const bf16x8 (&qf)[4], const unsigned char* sv, float cbias, int h, int lq,
;                       f32x16 (&O)[4], float& m, float& l) {
;     ...
;   f32x16 S0 = zero16(), S1 = zero16();
; #pragma unroll
;   for (int s = 0; s < 4; ++s) {
;     bf16x8 k0 = *(const bf16x8*)(sk + lq * 144 + (16 * s + 8 * h) * 2);
;     bf16x8 k1 = *(const bf16x8*)(sk + (32 + lq) * 144 + (16 * s + 8 * h) * 2);
;     S0 = mfma32(k0, qf[s], S0);
;     S1 = mfma32(k1, qf[s], S1);
;   }
;   float mx = fmaxf(fmaxf(S0[0], S0[1]), S0[2]);
; #pragma unroll
;   for (int i = 3; i < 15; i += 2) mx = fmaxf(fmaxf(mx, S0[i]), S0[i + 1]);
;   mx = fmaxf(mx, S0[15]);
; #pragma unroll
;   for (int i = 0; i < 16; i += 2) mx = fmaxf(fmaxf(mx, S1[i]), S1[i + 1]);
;   mx = fmaxf(mx, __shfl_xor(mx, 32));
;   const float mn = fmaxf(m, mx * csc + cbias);
;   if (__any(mn > m + 8.f)) {
;     const float a = __builtin_amdgcn_exp2f(m - mn);
;     l *= a; m = mn;
; #pragma unroll
;     for (int d = 0; d < 4; ++d) O[d] *= a;
;   }
.LBB0_938:
	ds_read_b128 v[178:181], v162
	ds_read_b128 v[182:185], v162 offset:32
	ds_read_b128 v[186:189], v162 offset:64
	ds_read_b128 v[190:193], v162 offset:96
	ds_read_b128 v[226:229], v162 offset:4608
	ds_read_b128 v[230:233], v162 offset:4640
	ds_read_b128 v[234:237], v162 offset:4672
	ds_read_b128 v[238:241], v162 offset:4704
	v_add3_u32 v144, s44, v0, v159
	s_waitcnt lgkmcnt(7)
	v_mfma_f32_32x32x16_bf16 v[66:81], v[178:181], v[98:101], 0
	ds_read_b128 v[178:181], v144 offset:18432
	s_waitcnt lgkmcnt(7)
	v_mfma_f32_32x32x16_bf16 v[66:81], v[182:185], v[102:105], v[66:81]
	ds_read_b128 v[182:185], v144 offset:23040
	s_waitcnt lgkmcnt(7)
	v_mfma_f32_32x32x16_bf16 v[66:81], v[186:189], v[106:109], v[66:81]
	ds_read_b128 v[186:189], v144 offset:27648
	s_waitcnt lgkmcnt(7)
	v_mfma_f32_32x32x16_bf16 v[66:81], v[190:193], v[110:113], v[66:81]
	ds_read_b128 v[190:193], v144 offset:32256
	s_waitcnt lgkmcnt(7)
	v_mfma_f32_32x32x16_bf16 v[82:97], v[226:229], v[98:101], 0
	ds_read_b128 v[226:229], v144 offset:18464
	s_waitcnt lgkmcnt(7)
	v_mfma_f32_32x32x16_bf16 v[82:97], v[230:233], v[102:105], v[82:97]
	ds_read_b128 v[230:233], v144 offset:23072
	s_waitcnt lgkmcnt(7)
	v_mfma_f32_32x32x16_bf16 v[82:97], v[234:237], v[106:109], v[82:97]
	ds_read_b128 v[234:237], v144 offset:27680
	s_waitcnt lgkmcnt(7)
	v_mfma_f32_32x32x16_bf16 v[82:97], v[238:241], v[110:113], v[82:97]
	ds_read_b128 v[238:241], v144 offset:32288
	s_nop 7
	v_max3_f32 v145, v66, v67, v68
	v_max3_f32 v145, v145, v69, v70
	v_max3_f32 v145, v145, v71, v72
	v_max3_f32 v145, v145, v73, v74
	v_max3_f32 v145, v145, v75, v76
	v_max3_f32 v145, v145, v77, v78
	v_max3_f32 v145, v145, v79, v80
	v_max_f32_e32 v145, v145, v81
	v_max3_f32 v145, v145, v82, v83
	v_max3_f32 v145, v145, v84, v85
	v_max3_f32 v145, v145, v86, v87
	v_max3_f32 v145, v145, v88, v89
	v_max3_f32 v145, v145, v90, v91
	v_max3_f32 v145, v145, v92, v93
	v_max3_f32 v145, v145, v94, v95
	v_max3_f32 v145, v145, v96, v97
	v_mov_b32_e32 v176, v145
	s_nop 1
	v_permlane32_swap_b32_e32 v176, v145
	v_add_f32_e32 v177, 0x41000000, v161
	v_max_f32_e32 v145, v145, v176
	v_fmamk_f32 v145, v145, 0x3e38aa3b, v155
	v_max_f32_e32 v145, v161, v145
	v_cmp_gt_f32_e32 vcc, v145, v177
	s_cbranch_vccz .LBB0_942
	v_sub_f32_e32 v176, v161, v145
	v_exp_f32_e32 v176, v176
	v_mov_b32_e32 v161, v145
	s_nop 0
	v_mul_f32_e32 v160, v160, v176
	v_pk_mul_f32 v[2:3], v[2:3], v[176:177] op_sel_hi:[1,0]
	v_pk_mul_f32 v[4:5], v[4:5], v[176:177] op_sel_hi:[1,0]
	v_pk_mul_f32 v[6:7], v[6:7], v[176:177] op_sel_hi:[1,0]
	v_pk_mul_f32 v[8:9], v[8:9], v[176:177] op_sel_hi:[1,0]
	v_pk_mul_f32 v[10:11], v[10:11], v[176:177] op_sel_hi:[1,0]
	v_pk_mul_f32 v[12:13], v[12:13], v[176:177] op_sel_hi:[1,0]
	v_pk_mul_f32 v[14:15], v[14:15], v[176:177] op_sel_hi:[1,0]
	v_pk_mul_f32 v[16:17], v[16:17], v[176:177] op_sel_hi:[1,0]
	v_pk_mul_f32 v[18:19], v[18:19], v[176:177] op_sel_hi:[1,0]
	v_pk_mul_f32 v[20:21], v[20:21], v[176:177] op_sel_hi:[1,0]
	v_pk_mul_f32 v[22:23], v[22:23], v[176:177] op_sel_hi:[1,0]
	v_pk_mul_f32 v[24:25], v[24:25], v[176:177] op_sel_hi:[1,0]
	v_pk_mul_f32 v[26:27], v[26:27], v[176:177] op_sel_hi:[1,0]
	v_pk_mul_f32 v[28:29], v[28:29], v[176:177] op_sel_hi:[1,0]
	v_pk_mul_f32 v[30:31], v[30:31], v[176:177] op_sel_hi:[1,0]
	v_pk_mul_f32 v[32:33], v[32:33], v[176:177] op_sel_hi:[1,0]
	v_pk_mul_f32 v[34:35], v[34:35], v[176:177] op_sel_hi:[1,0]
	v_pk_mul_f32 v[36:37], v[36:37], v[176:177] op_sel_hi:[1,0]
	v_pk_mul_f32 v[38:39], v[38:39], v[176:177] op_sel_hi:[1,0]
	v_pk_mul_f32 v[40:41], v[40:41], v[176:177] op_sel_hi:[1,0]
	v_pk_mul_f32 v[42:43], v[42:43], v[176:177] op_sel_hi:[1,0]
	v_pk_mul_f32 v[44:45], v[44:45], v[176:177] op_sel_hi:[1,0]
	v_pk_mul_f32 v[46:47], v[46:47], v[176:177] op_sel_hi:[1,0]
	v_pk_mul_f32 v[48:49], v[48:49], v[176:177] op_sel_hi:[1,0]
	v_pk_mul_f32 v[50:51], v[50:51], v[176:177] op_sel_hi:[1,0]
	v_pk_mul_f32 v[52:53], v[52:53], v[176:177] op_sel_hi:[1,0]
	v_pk_mul_f32 v[54:55], v[54:55], v[176:177] op_sel_hi:[1,0]
	v_pk_mul_f32 v[56:57], v[56:57], v[176:177] op_sel_hi:[1,0]
	v_pk_mul_f32 v[58:59], v[58:59], v[176:177] op_sel_hi:[1,0]
	v_pk_mul_f32 v[60:61], v[60:61], v[176:177] op_sel_hi:[1,0]
	v_pk_mul_f32 v[62:63], v[62:63], v[176:177] op_sel_hi:[1,0]
	v_pk_mul_f32 v[64:65], v[64:65], v[176:177] op_sel_hi:[1,0]
	s_branch .LBB0_943

; DI f32x16 mfma32(bf16x8 a, bf16x8 b, f32x16 c) { return __builtin_amdgcn_mfma_f32_32x32x16_bf16(a, b, c, 0, 0, 0); }
; DI void diff_map_far2(const unsigned char* sk, const bf16x8 (&qf)[4], const unsigned char* sv, float cbias, int h, int lq,
;                       f32x16 (&O)[4], float& m, float& l) {
;     ...
;   const float off = cbias - m;
;   float la = 0.f, lb = 0.f;
; #pragma unroll
;   for (int i = 0; i < 16; ++i) {
;     float pa = __builtin_amdgcn_exp2f(S0[i] * csc + off), pb = __builtin_amdgcn_exp2f(S1[i] * csc + off);
;     la += pa; lb += pb; S0[i] = pa; S1[i] = pb;
;   }
;   l += la + lb;
;   const bf16x8 p0 = pack8(S0, 0), p1 = pack8(S0, 1), p2 = pack8(S1, 0), p3 = pack8(S1, 1);
; #pragma unroll
;   for (int d = 0; d < 4; ++d) {
;     const unsigned char* vr = sv + (d * 32 + lq) * 144 + 16 * h;
;     bf16x8 v0 = *(const bf16x8*)(vr), v1 = *(const bf16x8*)(vr + 32), v2 = *(const bf16x8*)(vr + 64), v3 = *(const bf16x8*)(vr + 96);
;     O[d] = mfma32(v0, p0, O[d]);
;     O[d] = mfma32(v1, p1, O[d]);
;     O[d] = mfma32(v2, p2, O[d]);
;     O[d] = mfma32(v3, p3, O[d]);
;   }
.LBB0_942:
.LBB0_943:
	v_sub_f32_e32 v176, v155, v161
	v_fmamk_f32 v66, v66, 0x3e38aa3b, v176
	v_exp_f32_e32 v66, v66
	v_fmamk_f32 v67, v67, 0x3e38aa3b, v176
	v_exp_f32_e32 v67, v67
	v_fmamk_f32 v68, v68, 0x3e38aa3b, v176
	v_exp_f32_e32 v68, v68
	v_add_f32_e32 v225, v66, v67
	v_cvt_pk_bf16_f32 v168, v66, v67
	v_fmamk_f32 v69, v69, 0x3e38aa3b, v176
	v_exp_f32_e32 v69, v69
	v_add_f32_e32 v225, v225, v68
	v_fmamk_f32 v70, v70, 0x3e38aa3b, v176
	v_exp_f32_e32 v70, v70
	v_add_f32_e32 v225, v225, v69
	v_cvt_pk_bf16_f32 v169, v68, v69
	v_fmamk_f32 v71, v71, 0x3e38aa3b, v176
	v_exp_f32_e32 v71, v71
	v_add_f32_e32 v225, v225, v70
	v_fmamk_f32 v72, v72, 0x3e38aa3b, v176
	v_exp_f32_e32 v72, v72
	v_add_f32_e32 v225, v225, v71
	v_cvt_pk_bf16_f32 v170, v70, v71
	v_fmamk_f32 v73, v73, 0x3e38aa3b, v176
	v_exp_f32_e32 v73, v73
	v_add_f32_e32 v225, v225, v72
	v_fmamk_f32 v74, v74, 0x3e38aa3b, v176
	v_exp_f32_e32 v74, v74
	v_add_f32_e32 v225, v225, v73
	v_cvt_pk_bf16_f32 v171, v72, v73
	v_fmamk_f32 v75, v75, 0x3e38aa3b, v176
	v_exp_f32_e32 v75, v75
	v_add_f32_e32 v225, v225, v74
	v_fmamk_f32 v76, v76, 0x3e38aa3b, v176
	v_exp_f32_e32 v76, v76
	v_add_f32_e32 v225, v225, v75
	v_cvt_pk_bf16_f32 v172, v74, v75
	v_fmamk_f32 v77, v77, 0x3e38aa3b, v176
	v_exp_f32_e32 v77, v77
	v_add_f32_e32 v225, v225, v76
	v_fmamk_f32 v78, v78, 0x3e38aa3b, v176
	v_exp_f32_e32 v78, v78
	v_add_f32_e32 v225, v225, v77
	v_cvt_pk_bf16_f32 v173, v76, v77
	v_fmamk_f32 v79, v79, 0x3e38aa3b, v176
	v_exp_f32_e32 v79, v79
	v_add_f32_e32 v225, v225, v78
	v_fmamk_f32 v80, v80, 0x3e38aa3b, v176
	v_exp_f32_e32 v80, v80
	v_add_f32_e32 v225, v225, v79
	v_cvt_pk_bf16_f32 v174, v78, v79
	v_fmamk_f32 v81, v81, 0x3e38aa3b, v176
	v_exp_f32_e32 v81, v81
	v_add_f32_e32 v225, v225, v80
	v_cvt_pk_bf16_f32 v175, v80, v81
	v_add_f32_e32 v225, v225, v81
	s_nop 0
	s_waitcnt lgkmcnt(7)
	v_mfma_f32_32x32x16_bf16 v[34:49], v[178:181], v[168:171], v[34:49]
	ds_read_b128 v[178:181], v144 offset:18496
	v_fmamk_f32 v82, v82, 0x3e38aa3b, v176
	v_exp_f32_e32 v82, v82
	v_fmamk_f32 v83, v83, 0x3e38aa3b, v176
	v_exp_f32_e32 v83, v83
	s_waitcnt lgkmcnt(4)
	v_mfma_f32_32x32x16_bf16 v[34:49], v[226:229], v[172:175], v[34:49]
	ds_read_b128 v[226:229], v144 offset:18528
	v_add_f32_e32 v254, v82, v83
	v_cvt_pk_bf16_f32 v248, v82, v83
	v_fmamk_f32 v84, v84, 0x3e38aa3b, v176
	v_exp_f32_e32 v84, v84
	v_fmamk_f32 v85, v85, 0x3e38aa3b, v176
	v_exp_f32_e32 v85, v85
	s_waitcnt lgkmcnt(8)
	v_mfma_f32_32x32x16_bf16 v[18:33], v[182:185], v[168:171], v[18:33]
	ds_read_b128 v[182:185], v144 offset:23104
	v_add_f32_e32 v254, v254, v84
	v_add_f32_e32 v254, v254, v85
	v_cvt_pk_bf16_f32 v249, v84, v85
	v_fmamk_f32 v86, v86, 0x3e38aa3b, v176
	v_exp_f32_e32 v86, v86
	v_fmamk_f32 v87, v87, 0x3e38aa3b, v176
	v_exp_f32_e32 v87, v87
	s_waitcnt lgkmcnt(5)
	v_mfma_f32_32x32x16_bf16 v[18:33], v[230:233], v[172:175], v[18:33]
	ds_read_b128 v[230:233], v144 offset:23136
	v_add_f32_e32 v254, v254, v86
	v_add_f32_e32 v254, v254, v87
	v_cvt_pk_bf16_f32 v250, v86, v87
	v_fmamk_f32 v88, v88, 0x3e38aa3b, v176
	v_exp_f32_e32 v88, v88
	v_fmamk_f32 v89, v89, 0x3e38aa3b, v176
	v_exp_f32_e32 v89, v89
	s_waitcnt lgkmcnt(9)
	v_mfma_f32_32x32x16_bf16 v[2:17], v[186:189], v[168:171], v[2:17]
	ds_read_b128 v[186:189], v144 offset:27712
	v_add_f32_e32 v254, v254, v88
	v_add_f32_e32 v254, v254, v89
	v_cvt_pk_bf16_f32 v251, v88, v89
	v_fmamk_f32 v90, v90, 0x3e38aa3b, v176
	v_exp_f32_e32 v90, v90
	v_fmamk_f32 v91, v91, 0x3e38aa3b, v176
	v_exp_f32_e32 v91, v91
	s_waitcnt lgkmcnt(6)
	v_mfma_f32_32x32x16_bf16 v[2:17], v[234:237], v[172:175], v[2:17]
	ds_read_b128 v[234:237], v144 offset:27744
	v_add_f32_e32 v254, v254, v90
	v_add_f32_e32 v254, v254, v91
	v_cvt_pk_bf16_f32 v162, v90, v91
	v_fmamk_f32 v92, v92, 0x3e38aa3b, v176
	v_exp_f32_e32 v92, v92
	v_fmamk_f32 v93, v93, 0x3e38aa3b, v176
	v_exp_f32_e32 v93, v93
	s_waitcnt lgkmcnt(10)
	v_mfma_f32_32x32x16_bf16 v[50:65], v[190:193], v[168:171], v[50:65]
	ds_read_b128 v[190:193], v144 offset:32320
	v_add_f32_e32 v254, v254, v92
	v_add_f32_e32 v254, v254, v93
	v_cvt_pk_bf16_f32 v163, v92, v93
	v_fmamk_f32 v94, v94, 0x3e38aa3b, v176
	v_exp_f32_e32 v94, v94
	v_fmamk_f32 v95, v95, 0x3e38aa3b, v176
	v_exp_f32_e32 v95, v95
	s_waitcnt lgkmcnt(7)
	v_mfma_f32_32x32x16_bf16 v[50:65], v[238:241], v[172:175], v[50:65]
	ds_read_b128 v[238:241], v144 offset:32352
	v_add_f32_e32 v254, v254, v94
	v_add_f32_e32 v254, v254, v95
	v_cvt_pk_bf16_f32 v164, v94, v95
	v_fmamk_f32 v96, v96, 0x3e38aa3b, v176
	v_exp_f32_e32 v96, v96
	v_fmamk_f32 v97, v97, 0x3e38aa3b, v176
	v_exp_f32_e32 v97, v97
	v_add_f32_e32 v254, v254, v96
	v_add_f32_e32 v254, v254, v97
	v_cvt_pk_bf16_f32 v165, v96, v97
	v_add_f32_e32 v225, v225, v254
	v_add_f32_e32 v160, v160, v225
	s_waitcnt lgkmcnt(7)
	v_mfma_f32_32x32x16_bf16 v[34:49], v[178:181], v[248:251], v[34:49]
	s_waitcnt lgkmcnt(6)
	v_mfma_f32_32x32x16_bf16 v[34:49], v[226:229], v[162:165], v[34:49]
	s_waitcnt lgkmcnt(5)
	v_mfma_f32_32x32x16_bf16 v[18:33], v[182:185], v[248:251], v[18:33]
	s_waitcnt lgkmcnt(4)
	v_mfma_f32_32x32x16_bf16 v[18:33], v[230:233], v[162:165], v[18:33]
	s_waitcnt lgkmcnt(3)
	v_mfma_f32_32x32x16_bf16 v[2:17], v[186:189], v[248:251], v[2:17]
	s_waitcnt lgkmcnt(2)
	v_mfma_f32_32x32x16_bf16 v[2:17], v[234:237], v[162:165], v[2:17]
	s_waitcnt lgkmcnt(1)
	v_mfma_f32_32x32x16_bf16 v[50:65], v[190:193], v[248:251], v[50:65]
	s_waitcnt lgkmcnt(0)
	v_mfma_f32_32x32x16_bf16 v[50:65], v[238:241], v[162:165], v[50:65]
	s_or_b64 exec, exec, s[2:3]
	s_cmp_eq_u32 s43, s42
	s_cbranch_scc1 .LBB0_945

; DI void diff_job8(const Params& p, int layer, int b, int head, int qb, unsigned char* smem) {
;     ...
;   if (map == 0) {
;     float ss = 0.f;
; #pragma unroll
;     for (int d = 0; d < 4; ++d)
; #pragma unroll
;       for (int g = 0; g < 4; ++g) {
;         const float4 v = *(const float4*)(X + 32 * d + 8 * g + 4 * h);
;         float y0 = O[d][4 * g] * il - v.x, y1 = O[d][4 * g + 1] * il - v.y, y2 = O[d][4 * g + 2] * il - v.z, y3 = O[d][4 * g + 3] * il - v.w;
;         O[d][4 * g] = y0; O[d][4 * g + 1] = y1; O[d][4 * g + 2] = y2; O[d][4 * g + 3] = y3;
;         ss += y0 * y0 + y1 * y1 + y2 * y2 + y3 * y3;
;       }
;     ss += __shfl_xor(ss, 32);
;     const float sc = rsqrtf(ss * (1.f / 128.f) + EPS) * (1.f - lam_init);
;     const float* sg = p.subln + layer * 128;
;     u16* yr = p.ydf + (size_t)(b * TP + tq) * 512 + head * 128;
.LBB0_947:
	s_or_b64 exec, exec, s[2:3]
	s_waitcnt lgkmcnt(0)
	s_barrier
	s_and_saveexec_b64 s[2:3], s[40:41]
	s_cbranch_execz .LBB0_357
	ds_read_b128 v[74:77], v100 offset:384
	ds_read_b128 v[78:81], v100 offset:416
	v_mov_b32_e32 v69, v54
	v_mov_b32_e32 v54, v51
	v_mov_b32_e32 v68, v50
	s_waitcnt lgkmcnt(1)
	v_mov_b32_e32 v70, v74
	s_waitcnt lgkmcnt(0)
	v_mov_b32_e32 v71, v78
	v_mov_b32_e32 v78, v75
	v_pk_fma_f32 v[74:75], v[54:55], v[66:67], v[78:79] op_sel_hi:[1,0,1] neg_lo:[0,0,1] neg_hi:[0,0,1]
	v_mov_b32_e32 v50, v52
	v_mov_b32_e32 v51, v56
	v_mov_b32_e32 v54, v76
	v_mov_b32_e32 v55, v80
	v_pk_fma_f32 v[70:71], v[68:69], v[66:67], v[70:71] op_sel_hi:[1,0,1] neg_lo:[0,0,1] neg_hi:[0,0,1]
	v_pk_fma_f32 v[68:69], v[50:51], v[66:67], v[54:55] op_sel_hi:[1,0,1] neg_lo:[0,0,1] neg_hi:[0,0,1]
	v_pk_mul_f32 v[50:51], v[74:75], v[74:75]
	v_mov_b32_e32 v56, v53
	v_mov_b32_e32 v80, v77
	v_pk_fma_f32 v[50:51], v[70:71], v[70:71], v[50:51]
	v_pk_fma_f32 v[72:73], v[56:57], v[66:67], v[80:81] op_sel_hi:[1,0,1] neg_lo:[0,0,1] neg_hi:[0,0,1]
	v_pk_fma_f32 v[50:51], v[68:69], v[68:69], v[50:51]
	v_mov_b32_e32 v54, v58
	v_pk_fma_f32 v[76:77], v[72:73], v[72:73], v[50:51]
	ds_read_b128 v[50:53], v100 offset:448
	ds_read_b128 v[78:81], v100 offset:480
	v_mov_b32_e32 v55, v62
	v_mov_b32_e32 v62, v59
	s_load_dwordx8 s[40:47], s[0:1], 0x148
	s_waitcnt lgkmcnt(0)
	v_mov_b32_e32 v56, v50
	v_mov_b32_e32 v57, v78
	v_pk_fma_f32 v[56:57], v[54:55], v[66:67], v[56:57] op_sel_hi:[1,0,1] neg_lo:[0,0,1] neg_hi:[0,0,1]
	v_mov_b32_e32 v78, v51
	v_mov_b32_e32 v51, v64
	v_mov_b32_e32 v55, v80
	v_mov_b32_e32 v64, v61
	v_mov_b32_e32 v80, v53
	v_pk_fma_f32 v[62:63], v[62:63], v[66:67], v[78:79] op_sel_hi:[1,0,1] neg_lo:[0,0,1] neg_hi:[0,0,1]
	v_pk_fma_f32 v[58:59], v[64:65], v[66:67], v[80:81] op_sel_hi:[1,0,1] neg_lo:[0,0,1] neg_hi:[0,0,1]
	ds_read_b128 v[78:81], v100
	ds_read_b128 v[84:87], v100 offset:32
	ds_read_b128 v[102:105], v100 offset:128
	v_mov_b32_e32 v50, v60
	v_mov_b32_e32 v54, v52
	v_pk_fma_f32 v[54:55], v[50:51], v[66:67], v[54:55] op_sel_hi:[1,0,1] neg_lo:[0,0,1] neg_hi:[0,0,1]
	v_pk_mul_f32 v[50:51], v[62:63], v[62:63]
	ds_read_b128 v[92:95], v100 offset:64
	ds_read_b128 v[96:99], v100 offset:96
	v_pk_fma_f32 v[50:51], v[56:57], v[56:57], v[50:51]
	s_waitcnt lgkmcnt(2)
	v_pk_fma_f32 v[20:21], v[20:21], v[66:67], v[104:105] op_sel_hi:[1,0,1] neg_lo:[0,0,1] neg_hi:[0,0,1]
	v_pk_fma_f32 v[18:19], v[18:19], v[66:67], v[102:103] op_sel_hi:[1,0,1] neg_lo:[0,0,1] neg_hi:[0,0,1]
	ds_read_b128 v[102:105], v100 offset:160
	v_pk_fma_f32 v[50:51], v[54:55], v[54:55], v[50:51]
	s_lshl_b32 s10, s31, 1
	v_pk_fma_f32 v[60:61], v[58:59], v[58:59], v[50:51]
	v_lshl_add_u64 v[50:51], v[132:133], 1, s[44:45]
	v_lshl_add_u64 v[88:89], v[50:51], 0, s[10:11]
	global_load_dwordx4 v[178:181], v0, s[54:55]
	global_load_dwordx4 v[182:185], v0, s[54:55] offset:32
	global_load_dwordx4 v[186:189], v0, s[54:55] offset:64
	global_load_dwordx4 v[190:193], v0, s[54:55] offset:96
	global_load_dwordx4 v[226:229], v0, s[54:55] offset:128
	global_load_dwordx4 v[230:233], v0, s[54:55] offset:160
	global_load_dwordx4 v[234:237], v0, s[54:55] offset:192
	global_load_dwordx4 v[238:241], v0, s[54:55] offset:224
	v_pk_fma_f32 v[64:65], v[34:35], v[66:67], v[78:79] op_sel_hi:[1,0,1] neg_lo:[0,0,1] neg_hi:[0,0,1]
	v_pk_fma_f32 v[78:79], v[38:39], v[66:67], v[84:85] op_sel_hi:[1,0,1] neg_lo:[0,0,1] neg_hi:[0,0,1]
	s_waitcnt lgkmcnt(2)
	v_pk_fma_f32 v[38:39], v[44:45], v[66:67], v[94:95] op_sel_hi:[1,0,1] neg_lo:[0,0,1] neg_hi:[0,0,1]
	s_waitcnt lgkmcnt(1)
	v_pk_fma_f32 v[44:45], v[48:49], v[66:67], v[98:99] op_sel_hi:[1,0,1] neg_lo:[0,0,1] neg_hi:[0,0,1]
	s_waitcnt lgkmcnt(0)
	v_pk_fma_f32 v[24:25], v[24:25], v[66:67], v[104:105] op_sel_hi:[1,0,1] neg_lo:[0,0,1] neg_hi:[0,0,1]
	v_pk_fma_f32 v[48:49], v[22:23], v[66:67], v[102:103] op_sel_hi:[1,0,1] neg_lo:[0,0,1] neg_hi:[0,0,1]
	ds_read_b128 v[102:105], v100 offset:192
	v_mov_b32_e32 v131, v1
	v_pk_fma_f32 v[36:37], v[36:37], v[66:67], v[80:81] op_sel_hi:[1,0,1] neg_lo:[0,0,1] neg_hi:[0,0,1]
	v_pk_mul_f32 v[82:83], v[64:65], v[64:65]
	v_lshl_add_u64 v[34:35], v[88:89], 0, v[130:131]
	s_waitcnt lgkmcnt(0)
	v_pk_fma_f32 v[22:23], v[28:29], v[66:67], v[104:105] op_sel_hi:[1,0,1] neg_lo:[0,0,1] neg_hi:[0,0,1]
	v_pk_fma_f32 v[26:27], v[26:27], v[66:67], v[102:103] op_sel_hi:[1,0,1] neg_lo:[0,0,1] neg_hi:[0,0,1]
	ds_read_b128 v[102:105], v100 offset:224
	v_mov_b32_e32 v84, v23
	v_pk_fma_f32 v[40:41], v[40:41], v[66:67], v[86:87] op_sel_hi:[1,0,1] neg_lo:[0,0,1] neg_hi:[0,0,1]
	v_pk_mul_f32 v[88:89], v[78:79], v[78:79]
	v_pk_fma_f32 v[42:43], v[42:43], v[66:67], v[92:93] op_sel_hi:[1,0,1] neg_lo:[0,0,1] neg_hi:[0,0,1]
	s_waitcnt lgkmcnt(0)
	v_pk_fma_f32 v[30:31], v[30:31], v[66:67], v[102:103] op_sel_hi:[1,0,1] neg_lo:[0,0,1] neg_hi:[0,0,1]
	v_pk_fma_f32 v[28:29], v[32:33], v[66:67], v[104:105] op_sel_hi:[1,0,1] neg_lo:[0,0,1] neg_hi:[0,0,1]
	v_mov_b32_e32 v104, v27
	v_mov_b32_e32 v105, v31
	v_mov_b32_e32 v102, v26
	v_mov_b32_e32 v103, v30
	v_pk_mul_f32 v[104:105], v[104:105], v[104:105]
	v_mov_b32_e32 v32, v22
	v_mov_b32_e32 v33, v28
	v_pk_fma_f32 v[102:103], v[102:103], v[102:103], v[104:105]
	v_mov_b32_e32 v85, v29
	v_pk_fma_f32 v[32:33], v[32:33], v[32:33], v[102:103]
	ds_read_b128 v[102:105], v100 offset:256
	v_pk_fma_f32 v[112:113], v[84:85], v[84:85], v[32:33]
	v_pk_mul_f32 v[80:81], v[36:37], v[36:37]
	v_pk_mul_f32 v[86:87], v[40:41], v[40:41]
	v_pk_mul_f32 v[92:93], v[42:43], v[42:43]
	s_waitcnt lgkmcnt(0)
; DI void diff_job8(const Params& p, int layer, int b, int head, int qb, unsigned char* smem) {
;     ...
;     ss += __shfl_xor(ss, 32);
;     const float sc = rsqrtf(ss * (1.f / 128.f) + EPS) * (1.f - lam_init);
;     const float* sg = p.subln + layer * 128;
;     u16* yr = p.ydf + (size_t)(b * TP + tq) * 512 + head * 128;
; #pragma unroll
;     for (int d = 0; d < 4; ++d)
; #pragma unroll
;       for (int g = 0; g < 4; ++g) {
;         const int dv = 32 * d + 8 * g + 4 * h;
;         const float4 g4 = *(const float4*)(sg + dv);
;         u32x2 pk = {pack2bf(O[d][4 * g] * sc * g4.x, O[d][4 * g + 1] * sc * g4.y),
;                     pack2bf(O[d][4 * g + 2] * sc * g4.z, O[d][4 * g + 3] * sc * g4.w)};
;         *(u32x2*)(yr + dv) = pk;
	v_pk_fma_f32 v[4:5], v[4:5], v[66:67], v[104:105] op_sel_hi:[1,0,1] neg_lo:[0,0,1] neg_hi:[0,0,1]
	v_pk_fma_f32 v[32:33], v[2:3], v[66:67], v[102:103] op_sel_hi:[1,0,1] neg_lo:[0,0,1] neg_hi:[0,0,1]
	ds_read_b128 v[102:105], v100 offset:288
	v_mov_b32_e32 v2, v4
	v_add_f32_e32 v88, v88, v89
	v_add_f32_e32 v82, v82, v83
	v_pk_mul_f32 v[90:91], v[38:39], v[38:39]
	s_waitcnt lgkmcnt(0)
	v_pk_fma_f32 v[84:85], v[6:7], v[66:67], v[102:103] op_sel_hi:[1,0,1] neg_lo:[0,0,1] neg_hi:[0,0,1]
	v_pk_fma_f32 v[8:9], v[8:9], v[66:67], v[104:105] op_sel_hi:[1,0,1] neg_lo:[0,0,1] neg_hi:[0,0,1]
	v_mov_b32_e32 v104, v33
	v_mov_b32_e32 v105, v85
	v_mov_b32_e32 v102, v32
	v_mov_b32_e32 v103, v84
	v_pk_mul_f32 v[104:105], v[104:105], v[104:105]
	v_mov_b32_e32 v3, v8
	v_pk_fma_f32 v[102:103], v[102:103], v[102:103], v[104:105]
	v_mov_b32_e32 v6, v5
	v_pk_fma_f32 v[2:3], v[2:3], v[2:3], v[102:103]
	ds_read_b128 v[102:105], v100 offset:320
	v_mov_b32_e32 v7, v9
	v_pk_fma_f32 v[46:47], v[46:47], v[66:67], v[96:97] op_sel_hi:[1,0,1] neg_lo:[0,0,1] neg_hi:[0,0,1]
	v_pk_fma_f32 v[2:3], v[6:7], v[6:7], v[2:3]
	v_add_f32_e32 v86, v86, v88
	s_waitcnt lgkmcnt(0)
	v_pk_fma_f32 v[10:11], v[10:11], v[66:67], v[102:103] op_sel_hi:[1,0,1] neg_lo:[0,0,1] neg_hi:[0,0,1]
	ds_read_b128 v[100:103], v100 offset:352
	v_pk_fma_f32 v[6:7], v[12:13], v[66:67], v[104:105] op_sel_hi:[1,0,1] neg_lo:[0,0,1] neg_hi:[0,0,1]
	v_add_f32_e32 v80, v80, v82
	v_add_f32_e32 v86, v87, v86
	v_add_f32_e32 v80, v81, v80
	s_waitcnt lgkmcnt(0)
	v_pk_fma_f32 v[12:13], v[16:17], v[66:67], v[102:103] op_sel_hi:[1,0,1] neg_lo:[0,0,1] neg_hi:[0,0,1]
	v_pk_fma_f32 v[14:15], v[14:15], v[66:67], v[100:101] op_sel_hi:[1,0,1] neg_lo:[0,0,1] neg_hi:[0,0,1]
	v_add_f32_e32 v66, v92, v93
	v_add_f32_e32 v66, v90, v66
	v_pk_mul_f32 v[96:97], v[46:47], v[46:47]
	v_add_f32_e32 v66, v91, v66
	v_add_f32_e32 v80, v80, v86
	v_pk_mul_f32 v[94:95], v[44:45], v[44:45]
	v_add_f32_e32 v66, v80, v66
	v_add_f32_e32 v80, v96, v97
	v_add_f32_e32 v80, v94, v80
	v_pk_mul_f32 v[106:107], v[18:19], v[18:19]
	v_add_f32_e32 v80, v95, v80
	v_pk_mul_f32 v[98:99], v[20:21], v[20:21]
	v_add_f32_e32 v66, v66, v80
	v_add_f32_e32 v80, v106, v107
	v_add_f32_e32 v80, v98, v80
	v_pk_mul_f32 v[110:111], v[48:49], v[48:49]
	v_add_f32_e32 v80, v99, v80
	v_pk_mul_f32 v[108:109], v[24:25], v[24:25]
	v_add_f32_e32 v66, v66, v80
	v_add_f32_e32 v80, v110, v111
	v_add_f32_e32 v80, v108, v80
	v_add_f32_e32 v80, v109, v80
	v_mov_b32_e32 v104, v11
	v_mov_b32_e32 v105, v15
	v_add_f32_e32 v66, v66, v80
	v_mov_b32_e32 v102, v10
	v_mov_b32_e32 v103, v14
	v_pk_mul_f32 v[104:105], v[104:105], v[104:105]
	v_add_f32_e32 v66, v66, v112
	v_mov_b32_e32 v16, v6
	v_mov_b32_e32 v17, v12
	v_pk_fma_f32 v[102:103], v[102:103], v[102:103], v[104:105]
	v_add_f32_e32 v66, v66, v113
	v_mov_b32_e32 v100, v7
	v_mov_b32_e32 v101, v13
	v_pk_fma_f32 v[16:17], v[16:17], v[16:17], v[102:103]
	v_add_f32_e32 v2, v66, v2
	v_pk_fma_f32 v[16:17], v[100:101], v[100:101], v[16:17]
	v_add_f32_e32 v2, v2, v3
	v_add_f32_e32 v2, v2, v16
	v_add_f32_e32 v2, v2, v17
	v_add_f32_e32 v2, v2, v76
	v_add_f32_e32 v2, v2, v77
	v_add_f32_e32 v2, v2, v60
	v_add_f32_e32 v2, v2, v61
	ds_bpermute_b32 v3, v67, v2
	s_waitcnt lgkmcnt(0)
	v_add_f32_e32 v2, v2, v3
	v_fmamk_f32 v2, v2, 0x3c000000, v199
	v_cmp_gt_f32_e32 vcc, s14, v2
	v_mul_f32_e32 v3, 0x4b800000, v2
	s_nop 0
	v_cndmask_b32_e32 v2, v2, v3, vcc
	v_rsq_f32_e32 v2, v2
	s_nop 0
	v_mul_f32_e32 v3, 0x45800000, v2
	v_cndmask_b32_e32 v2, v2, v3, vcc
	v_mul_f32_e32 v2, v147, v2
	v_pk_mul_f32 v[16:17], v[64:65], v[2:3] op_sel_hi:[1,0]
	v_pk_mul_f32 v[36:37], v[36:37], v[2:3] op_sel_hi:[1,0]
	s_waitcnt vmcnt(7)
	v_pk_mul_f32 v[16:17], v[178:179], v[16:17]
	v_pk_mul_f32 v[36:37], v[180:181], v[36:37]
	v_cvt_pk_bf16_f32 v16, v16, v17
	v_cvt_pk_bf16_f32 v17, v36, v37
	global_store_dwordx2 v[34:35], v[16:17], off
	global_load_dwordx4 v[178:181], v0, s[54:55] offset:256
	v_pk_mul_f32 v[16:17], v[78:79], v[2:3] op_sel_hi:[1,0]
	v_pk_mul_f32 v[36:37], v[40:41], v[2:3] op_sel_hi:[1,0]
	v_pk_mul_f32 v[4:5], v[4:5], v[2:3] op_sel_hi:[1,0]
	v_pk_mul_f32 v[8:9], v[8:9], v[2:3] op_sel_hi:[1,0]
	v_pk_mul_f32 v[6:7], v[6:7], v[2:3] op_sel_hi:[1,0]
	s_waitcnt vmcnt(8)
	v_pk_mul_f32 v[16:17], v[182:183], v[16:17]
	v_pk_mul_f32 v[36:37], v[184:185], v[36:37]
	v_cvt_pk_bf16_f32 v16, v16, v17
	v_cvt_pk_bf16_f32 v17, v36, v37
	global_store_dwordx2 v[34:35], v[16:17], off offset:16
	global_load_dwordx4 v[182:185], v0, s[54:55] offset:288
	v_pk_mul_f32 v[16:17], v[42:43], v[2:3] op_sel_hi:[1,0]
	v_pk_mul_f32 v[36:37], v[38:39], v[2:3] op_sel_hi:[1,0]
	s_waitcnt vmcnt(9)
	v_pk_mul_f32 v[16:17], v[186:187], v[16:17]
	v_pk_mul_f32 v[36:37], v[36:37], v[188:189]
	v_cvt_pk_bf16_f32 v16, v16, v17
	v_cvt_pk_bf16_f32 v17, v36, v37
	global_store_dwordx2 v[34:35], v[16:17], off offset:32
	global_load_dwordx4 v[186:189], v0, s[54:55] offset:320
	v_pk_mul_f32 v[16:17], v[46:47], v[2:3] op_sel_hi:[1,0]
	s_waitcnt vmcnt(10)
; DI void diff_job8(const Params& p, int layer, int b, int head, int qb, unsigned char* smem) {
;     ...
; #pragma unroll
;     for (int d = 0; d < 4; ++d)
; #pragma unroll
;       for (int g = 0; g < 4; ++g) {
;         const int dv = 32 * d + 8 * g + 4 * h;
;         const float4 g4 = *(const float4*)(sg + dv);
;         u32x2 pk = {pack2bf(O[d][4 * g] * sc * g4.x, O[d][4 * g + 1] * sc * g4.y),
;                     pack2bf(O[d][4 * g + 2] * sc * g4.z, O[d][4 * g + 3] * sc * g4.w)};
;         *(u32x2*)(yr + dv) = pk;
	v_pk_mul_f32 v[16:17], v[16:17], v[190:191]
	v_pk_mul_f32 v[36:37], v[44:45], v[2:3] op_sel_hi:[1,0]
	v_cvt_pk_bf16_f32 v16, v16, v17
	v_pk_mul_f32 v[36:37], v[36:37], v[192:193]
	s_nop 0
	v_cvt_pk_bf16_f32 v17, v36, v37
	global_store_dwordx2 v[34:35], v[16:17], off offset:48
	global_load_dwordx4 v[190:193], v0, s[54:55] offset:352
	v_pk_mul_f32 v[16:17], v[18:19], v[2:3] op_sel_hi:[1,0]
	v_pk_mul_f32 v[18:19], v[20:21], v[2:3] op_sel_hi:[1,0]
	v_pk_mul_f32 v[20:21], v[48:49], v[2:3] op_sel_hi:[1,0]
	s_waitcnt vmcnt(11)
	v_pk_mul_f32 v[16:17], v[16:17], v[226:227]
	v_pk_mul_f32 v[18:19], v[18:19], v[228:229]
	v_cvt_pk_bf16_f32 v16, v16, v17
	v_cvt_pk_bf16_f32 v17, v18, v19
	global_store_dwordx2 v[34:35], v[16:17], off offset:64
	global_load_dwordx4 v[226:229], v0, s[54:55] offset:384
	s_waitcnt vmcnt(12)
	v_pk_mul_f32 v[16:17], v[20:21], v[230:231]
	v_pk_mul_f32 v[20:21], v[24:25], v[2:3] op_sel_hi:[1,0]
	v_cvt_pk_bf16_f32 v16, v16, v17
	v_pk_mul_f32 v[18:19], v[20:21], v[232:233]
	v_pk_mul_f32 v[20:21], v[26:27], v[2:3] op_sel_hi:[1,0]
	v_cvt_pk_bf16_f32 v17, v18, v19
	global_store_dwordx2 v[34:35], v[16:17], off offset:80
	global_load_dwordx4 v[230:233], v0, s[54:55] offset:416
	s_waitcnt vmcnt(13)
	v_pk_mul_f32 v[16:17], v[20:21], v[234:235]
	v_pk_mul_f32 v[20:21], v[22:23], v[2:3] op_sel_hi:[1,0]
	v_cvt_pk_bf16_f32 v16, v16, v17
	v_pk_mul_f32 v[18:19], v[20:21], v[236:237]
	v_pk_mul_f32 v[20:21], v[30:31], v[2:3] op_sel_hi:[1,0]
	v_cvt_pk_bf16_f32 v17, v18, v19
	global_store_dwordx2 v[34:35], v[16:17], off offset:96
	global_load_dwordx4 v[234:237], v0, s[54:55] offset:448
	s_waitcnt vmcnt(14)
	v_pk_mul_f32 v[16:17], v[20:21], v[238:239]
	v_pk_mul_f32 v[20:21], v[28:29], v[2:3] op_sel_hi:[1,0]
	v_cvt_pk_bf16_f32 v16, v16, v17
	v_pk_mul_f32 v[18:19], v[20:21], v[240:241]
	v_pk_mul_f32 v[20:21], v[32:33], v[2:3] op_sel_hi:[1,0]
	v_cvt_pk_bf16_f32 v17, v18, v19
	global_store_dwordx2 v[34:35], v[16:17], off offset:112
	global_load_dwordx4 v[238:241], v0, s[54:55] offset:480
	s_waitcnt vmcnt(14)
	v_pk_mul_f32 v[16:17], v[20:21], v[178:179]
	v_pk_mul_f32 v[4:5], v[4:5], v[180:181]
	v_cvt_pk_bf16_f32 v16, v16, v17
	v_cvt_pk_bf16_f32 v17, v4, v5
	global_store_dwordx2 v[34:35], v[16:17], off offset:128
	v_pk_mul_f32 v[4:5], v[84:85], v[2:3] op_sel_hi:[1,0]
	s_waitcnt vmcnt(13)
	v_pk_mul_f32 v[8:9], v[8:9], v[184:185]
	v_pk_mul_f32 v[4:5], v[4:5], v[182:183]
	s_nop 0
	v_cvt_pk_bf16_f32 v4, v4, v5
	v_cvt_pk_bf16_f32 v5, v8, v9
	global_store_dwordx2 v[34:35], v[4:5], off offset:144
	v_pk_mul_f32 v[4:5], v[10:11], v[2:3] op_sel_hi:[1,0]
	v_pk_mul_f32 v[8:9], v[14:15], v[2:3] op_sel_hi:[1,0]
	s_waitcnt vmcnt(12)
	v_pk_mul_f32 v[4:5], v[4:5], v[186:187]
	v_pk_mul_f32 v[6:7], v[6:7], v[188:189]
	v_cvt_pk_bf16_f32 v4, v4, v5
	v_cvt_pk_bf16_f32 v5, v6, v7
	global_store_dwordx2 v[34:35], v[4:5], off offset:160
	s_waitcnt vmcnt(11)
	v_pk_mul_f32 v[4:5], v[8:9], v[190:191]
	v_pk_mul_f32 v[8:9], v[12:13], v[2:3] op_sel_hi:[1,0]
	v_cvt_pk_bf16_f32 v4, v4, v5
	v_pk_mul_f32 v[6:7], v[8:9], v[192:193]
	v_mov_b32_e32 v8, v70
	v_cvt_pk_bf16_f32 v5, v6, v7
	global_store_dwordx2 v[34:35], v[4:5], off offset:176
	v_mov_b32_e32 v9, v74
	v_pk_mul_f32 v[8:9], v[8:9], v[2:3] op_sel_hi:[1,0]
	v_mov_b32_e32 v74, v71
	s_waitcnt vmcnt(10)
	v_pk_mul_f32 v[4:5], v[8:9], v[226:227]
	v_mov_b32_e32 v8, v68
	v_mov_b32_e32 v9, v72
	v_pk_mul_f32 v[8:9], v[8:9], v[2:3] op_sel_hi:[1,0]
	v_cvt_pk_bf16_f32 v4, v4, v5
	v_pk_mul_f32 v[6:7], v[8:9], v[228:229]
	v_pk_mul_f32 v[8:9], v[74:75], v[2:3] op_sel_hi:[1,0]
	v_cvt_pk_bf16_f32 v5, v6, v7
	global_store_dwordx2 v[34:35], v[4:5], off offset:192
	v_mov_b32_e32 v72, v69
	s_waitcnt vmcnt(9)
	v_pk_mul_f32 v[4:5], v[8:9], v[230:231]
	v_pk_mul_f32 v[8:9], v[72:73], v[2:3] op_sel_hi:[1,0]
	v_cvt_pk_bf16_f32 v4, v4, v5
	v_pk_mul_f32 v[6:7], v[8:9], v[232:233]
	v_mov_b32_e32 v8, v56
	v_cvt_pk_bf16_f32 v5, v6, v7
	global_store_dwordx2 v[34:35], v[4:5], off offset:208
	v_mov_b32_e32 v9, v62
	v_pk_mul_f32 v[8:9], v[8:9], v[2:3] op_sel_hi:[1,0]
	v_mov_b32_e32 v62, v57
	s_waitcnt vmcnt(8)
	v_pk_mul_f32 v[4:5], v[8:9], v[234:235]
	v_mov_b32_e32 v8, v54
	v_mov_b32_e32 v9, v58
	v_pk_mul_f32 v[8:9], v[8:9], v[2:3] op_sel_hi:[1,0]
	v_cvt_pk_bf16_f32 v4, v4, v5
	v_pk_mul_f32 v[6:7], v[8:9], v[236:237]
	v_mov_b32_e32 v58, v55
	v_cvt_pk_bf16_f32 v5, v6, v7
	global_store_dwordx2 v[34:35], v[4:5], off offset:224
	v_pk_mul_f32 v[8:9], v[62:63], v[2:3] op_sel_hi:[1,0]
	v_pk_mul_f32 v[2:3], v[58:59], v[2:3] op_sel_hi:[1,0]
	s_waitcnt vmcnt(7)
	v_pk_mul_f32 v[4:5], v[8:9], v[238:239]
	v_pk_mul_f32 v[2:3], v[2:3], v[240:241]
	v_cvt_pk_bf16_f32 v4, v4, v5
	v_cvt_pk_bf16_f32 v5, v2, v3
	global_store_dwordx2 v[34:35], v[4:5], off offset:240
	s_branch .LBB0_357
